# in-projection q/k rotary epilogue rewritten by hand: rope-table rows fetched three row groups ahead with counted waits
# baseline (speedup 1.0000x reference)
; #define PG8_STAGE(bufoff, gbase, voff) do { _Pragma("unroll") for (int _i = 0; _i < 2; ++_i) \
;         __builtin_amdgcn_global_load_lds((const unsigned*)((const char*)(gbase) + (voff)[_i]), (PG8_LAS unsigned*)(lds + (bufoff) + ldsw + _i * 8192), 16, 0, 0); } while (0)
; #define PG8_LDA(dst, b, h) do { _Pragma("unroll") for (int m = 0; m < 4; ++m) _Pragma("unroll") for (int k = 0; k < 2; ++k) dst[m][k] = *(const PG8_LAS bf16x8*)(lds + PG8_SA(b, h) + aoff + m * 2048 + k * 1024); } while (0)
; #define PG8_LDB(dst, b, h) do { _Pragma("unroll") for (int n = 0; n < 2; ++n) _Pragma("unroll") for (int k = 0; k < 2; ++k) dst[n][k] = *(const PG8_LAS bf16x8*)(lds + PG8_SB(b, h) + boff + n * 2048 + k * 1024); } while (0)
; #define PG8_MMA(ai, bj, At, Bt) do { __builtin_amdgcn_s_setprio(1); _Pragma("unroll") for (int m = 0; m < 4; ++m) _Pragma("unroll") for (int n = 0; n < 2; ++n) _Pragma("unroll") for (int k = 0; k < 2; ++k) \
;         acc[ai][bj][m][n] = __builtin_amdgcn_mfma_f32_16x16x32_bf16(Bt[n][k], At[m][k], acc[ai][bj][m][n], 0, 0, 0); __builtin_amdgcn_s_setprio(0); } while (0)
; #define PG8_WAIT_V(n) asm volatile("s_waitcnt vmcnt(" #n ")" ::: "memory")
; template <class Epi, class Sched, bool ALIGN_EPI = false, bool SP2 = false>
; __device__ __forceinline__ void gemm_phase(PG8_LAS unsigned char* lds, const Gemm g, const Sched& S, const Epi& E) {
;     ...
;             PG8_LDB(B0, 0, 0); PG8_LDB(B1, 0, 1); PG8_SCHED; PG8_LDA(At, 0, 0); PG8_STAGE(PG8_SA(1, 1), a1 + hstep, voffA);
;             PG8_WAIT_V(8); PG8_WAIT_L(0); PG8_BAR; PG8_MMA(0, 0, At, B0); PG8_MMA(0, 1, At, B1); PG8_BAR; PG8_SCHED;
;             PG8_LDA(At, 0, 1); PG8_STAGE(PG8_SB(0, 0), b2, voffB); PG8_STAGE(PG8_SB(0, 1), b2 + hstep, voffB); PG8_STAGE(PG8_SA(0, 0), a2, voffA);
;             PG8_WAIT_V(8); PG8_WAIT_L(0); PG8_BAR; PG8_MMA(1, 0, At, B0); PG8_MMA(1, 1, At, B1); PG8_BAR; PG8_SCHED;
;             PG8_LDB(B0, 1, 0); PG8_LDB(B1, 1, 1); PG8_SCHED; PG8_LDA(At, 1, 0); PG8_STAGE(PG8_SA(0, 1), a2 + hstep, voffA);
;             PG8_WAIT_V(8); PG8_WAIT_L(0); PG8_BAR; PG8_MMA(0, 0, At, B0); PG8_MMA(0, 1, At, B1); PG8_BAR; PG8_SCHED;
;             PG8_LDA(At, 1, 1); PG8_STAGE(PG8_SB(1, 0), b3, voffB); PG8_STAGE(PG8_SB(1, 1), b3 + hstep, voffB); PG8_STAGE(PG8_SA(1, 0), a3, voffA);
;             PG8_WAIT_V(8); PG8_WAIT_L(0); PG8_BAR; PG8_MMA(1, 0, At, B0); PG8_MMA(1, 1, At, B1); PG8_BAR; PG8_SCHED;
.LBB0_133:
	s_add_u32 s18, s16, 0xfffc0080
	s_addc_u32 s19, s17, -1
	s_add_i32 s41, 0, 0x10000
	s_cmp_eq_u32 s40, 12
	s_cselect_b32 s21, s1, s19
	s_cselect_b32 s20, s11, s18
	v_add_u32_e32 v156, s41, v159
	s_cselect_b32 s19, s9, s39
	s_cselect_b32 s18, s33, s38
	s_add_i32 s44, 0, 0x14000
	ds_read_b128 v[144:147], v156
	ds_read_b128 v[148:151], v156 offset:1024
	ds_read_b128 v[152:155], v156 offset:2048
	ds_read_b128 v[162:165], v156 offset:3072
	v_add_u32_e32 v156, s44, v159
	ds_read_b128 v[166:169], v156
	ds_read_b128 v[170:173], v156 offset:1024
	ds_read_b128 v[174:177], v156 offset:2048
	ds_read_b128 v[178:181], v156 offset:3072
	v_lshl_add_u64 v[156:157], s[16:17], 0, v[140:141]
	s_add_i32 m0, s24, 0xc000
	ds_read_b128 v[182:185], v161
	ds_read_b128 v[194:197], v161 offset:1024
	ds_read_b128 v[198:201], v161 offset:2048
	ds_read_b128 v[202:205], v161 offset:3072
	ds_read_b128 v[210:213], v161 offset:4096
	ds_read_b128 v[214:217], v161 offset:5120
	ds_read_b128 v[218:221], v161 offset:6144
	ds_read_b128 v[222:225], v161 offset:7168
	global_load_lds_dwordx4 v[156:157], off
	v_lshl_add_u64 v[156:157], s[16:17], 0, v[142:143]
	s_add_i32 m0, s24, 0xe000
	s_nop 0
	global_load_lds_dwordx4 v[156:157], off
	s_waitcnt vmcnt(8)
	s_waitcnt lgkmcnt(0)
	s_barrier
	s_setprio 1
	s_waitcnt lgkmcnt(0)
	v_mfma_f32_16x16x32_bf16 v[124:127], v[144:147], v[182:185], v[124:127]
	v_mfma_f32_16x16x32_bf16 v[120:123], v[152:155], v[182:185], v[120:123]
	v_mfma_f32_16x16x32_bf16 v[108:111], v[144:147], v[198:201], v[108:111]
	v_mfma_f32_16x16x32_bf16 v[104:107], v[152:155], v[198:201], v[104:107]
	v_mfma_f32_16x16x32_bf16 v[92:95], v[144:147], v[210:213], v[92:95]
	v_mfma_f32_16x16x32_bf16 v[88:91], v[152:155], v[210:213], v[88:91]
	v_mfma_f32_16x16x32_bf16 v[76:79], v[144:147], v[218:221], v[76:79]
	v_mfma_f32_16x16x32_bf16 v[72:75], v[152:155], v[218:221], v[72:75]
	v_mfma_f32_16x16x32_bf16 v[124:127], v[148:151], v[194:197], v[124:127]
	v_mfma_f32_16x16x32_bf16 v[120:123], v[162:165], v[194:197], v[120:123]
	v_mfma_f32_16x16x32_bf16 v[108:111], v[148:151], v[202:205], v[108:111]
	v_mfma_f32_16x16x32_bf16 v[104:107], v[162:165], v[202:205], v[104:107]
	v_mfma_f32_16x16x32_bf16 v[92:95], v[148:151], v[214:217], v[92:95]
	v_mfma_f32_16x16x32_bf16 v[88:91], v[162:165], v[214:217], v[88:91]
	v_mfma_f32_16x16x32_bf16 v[76:79], v[148:151], v[222:225], v[76:79]
	v_mfma_f32_16x16x32_bf16 v[72:75], v[162:165], v[222:225], v[72:75]
	s_setprio 0
	s_setprio 1
	v_mfma_f32_16x16x32_bf16 v[116:119], v[166:169], v[182:185], v[116:119]
	v_mfma_f32_16x16x32_bf16 v[112:115], v[174:177], v[182:185], v[112:115]
	v_mfma_f32_16x16x32_bf16 v[100:103], v[166:169], v[198:201], v[100:103]
	v_mfma_f32_16x16x32_bf16 v[96:99], v[174:177], v[198:201], v[96:99]
	v_mfma_f32_16x16x32_bf16 v[84:87], v[166:169], v[210:213], v[84:87]
	v_mfma_f32_16x16x32_bf16 v[80:83], v[174:177], v[210:213], v[80:83]
	v_mfma_f32_16x16x32_bf16 v[68:71], v[166:169], v[218:221], v[68:71]
	v_mfma_f32_16x16x32_bf16 v[64:67], v[174:177], v[218:221], v[64:67]
	v_mfma_f32_16x16x32_bf16 v[116:119], v[170:173], v[194:197], v[116:119]
	v_mfma_f32_16x16x32_bf16 v[112:115], v[178:181], v[194:197], v[112:115]
	v_mfma_f32_16x16x32_bf16 v[100:103], v[170:173], v[202:205], v[100:103]
	v_mfma_f32_16x16x32_bf16 v[96:99], v[178:181], v[202:205], v[96:99]
	v_mfma_f32_16x16x32_bf16 v[84:87], v[170:173], v[214:217], v[84:87]
	v_mfma_f32_16x16x32_bf16 v[80:83], v[178:181], v[214:217], v[80:83]
	v_mfma_f32_16x16x32_bf16 v[68:71], v[170:173], v[222:225], v[68:71]
	v_mfma_f32_16x16x32_bf16 v[64:67], v[178:181], v[222:225], v[64:67]
	s_setprio 0
	s_barrier
	s_add_i32 s41, s41, s23
	v_lshl_add_u64 v[156:157], s[18:19], 0, v[130:131]
	s_mov_b32 m0, s41
	ds_read_b128 v[182:185], v161 offset:16384
	ds_read_b128 v[194:197], v161 offset:17408
	ds_read_b128 v[198:201], v161 offset:18432
	ds_read_b128 v[202:205], v161 offset:19456
	ds_read_b128 v[210:213], v161 offset:20480
	ds_read_b128 v[214:217], v161 offset:21504
	ds_read_b128 v[218:221], v161 offset:22528
	ds_read_b128 v[222:225], v161 offset:23552
	global_load_lds_dwordx4 v[156:157], off
	s_add_i32 m0, s41, 0x2000
	s_add_u32 s42, s18, 0x40000
	v_lshl_add_u64 v[186:187], s[18:19], 0, v[134:135]
	s_addc_u32 s43, s19, 0
	s_add_i32 s41, s44, s23
	global_load_lds_dwordx4 v[186:187], off
	v_lshl_add_u64 v[190:191], s[42:43], 0, v[130:131]
	s_mov_b32 m0, s41
	v_lshl_add_u64 v[226:227], s[20:21], 0, v[132:133]
	global_load_lds_dwordx4 v[190:191], off
	v_lshl_add_u64 v[190:191], s[42:43], 0, v[134:135]
	s_add_i32 m0, s41, 0x2000
	s_nop 0
	global_load_lds_dwordx4 v[190:191], off
	v_lshl_add_u64 v[190:191], s[20:21], 0, v[128:129]
	s_mov_b32 m0, s24
	s_nop 0
	global_load_lds_dwordx4 v[190:191], off
	s_mov_b32 m0, s25
	s_nop 0
	global_load_lds_dwordx4 v[226:227], off
	s_waitcnt vmcnt(8)
	s_waitcnt lgkmcnt(0)
	s_barrier
; #define PG8_STAGE(bufoff, gbase, voff) do { _Pragma("unroll") for (int _i = 0; _i < 2; ++_i) \
;         __builtin_amdgcn_global_load_lds((const unsigned*)((const char*)(gbase) + (voff)[_i]), (PG8_LAS unsigned*)(lds + (bufoff) + ldsw + _i * 8192), 16, 0, 0); } while (0)
; #define PG8_LDA(dst, b, h) do { _Pragma("unroll") for (int m = 0; m < 4; ++m) _Pragma("unroll") for (int k = 0; k < 2; ++k) dst[m][k] = *(const PG8_LAS bf16x8*)(lds + PG8_SA(b, h) + aoff + m * 2048 + k * 1024); } while (0)
; #define PG8_LDB(dst, b, h) do { _Pragma("unroll") for (int n = 0; n < 2; ++n) _Pragma("unroll") for (int k = 0; k < 2; ++k) dst[n][k] = *(const PG8_LAS bf16x8*)(lds + PG8_SB(b, h) + boff + n * 2048 + k * 1024); } while (0)
; #define PG8_MMA(ai, bj, At, Bt) do { __builtin_amdgcn_s_setprio(1); _Pragma("unroll") for (int m = 0; m < 4; ++m) _Pragma("unroll") for (int n = 0; n < 2; ++n) _Pragma("unroll") for (int k = 0; k < 2; ++k) \
;         acc[ai][bj][m][n] = __builtin_amdgcn_mfma_f32_16x16x32_bf16(Bt[n][k], At[m][k], acc[ai][bj][m][n], 0, 0, 0); __builtin_amdgcn_s_setprio(0); } while (0)
; #define PG8_WAIT_V(n) asm volatile("s_waitcnt vmcnt(" #n ")" ::: "memory")
; template <class Epi, class Sched, bool ALIGN_EPI = false, bool SP2 = false>
; __device__ __forceinline__ void gemm_phase(PG8_LAS unsigned char* lds, const Gemm g, const Sched& S, const Epi& E) {
;     ...
;             PG8_LDB(B0, 0, 0); PG8_LDB(B1, 0, 1); PG8_SCHED; PG8_LDA(At, 0, 0); PG8_STAGE(PG8_SA(1, 1), a1 + hstep, voffA);
;             PG8_WAIT_V(8); PG8_WAIT_L(0); PG8_BAR; PG8_MMA(0, 0, At, B0); PG8_MMA(0, 1, At, B1); PG8_BAR; PG8_SCHED;
;             PG8_LDA(At, 0, 1); PG8_STAGE(PG8_SB(0, 0), b2, voffB); PG8_STAGE(PG8_SB(0, 1), b2 + hstep, voffB); PG8_STAGE(PG8_SA(0, 0), a2, voffA);
;             PG8_WAIT_V(8); PG8_WAIT_L(0); PG8_BAR; PG8_MMA(1, 0, At, B0); PG8_MMA(1, 1, At, B1); PG8_BAR; PG8_SCHED;
;             PG8_LDB(B0, 1, 0); PG8_LDB(B1, 1, 1); PG8_SCHED; PG8_LDA(At, 1, 0); PG8_STAGE(PG8_SA(0, 1), a2 + hstep, voffA);
;             PG8_WAIT_V(8); PG8_WAIT_L(0); PG8_BAR; PG8_MMA(0, 0, At, B0); PG8_MMA(0, 1, At, B1); PG8_BAR; PG8_SCHED;
;             PG8_LDA(At, 1, 1); PG8_STAGE(PG8_SB(1, 0), b3, voffB); PG8_STAGE(PG8_SB(1, 1), b3 + hstep, voffB); PG8_STAGE(PG8_SA(1, 0), a3, voffA);
;             PG8_WAIT_V(8); PG8_WAIT_L(0); PG8_BAR; PG8_MMA(1, 0, At, B0); PG8_MMA(1, 1, At, B1); PG8_BAR; PG8_SCHED;
	s_setprio 1
	s_waitcnt lgkmcnt(0)
	v_mfma_f32_16x16x32_bf16 v[60:63], v[144:147], v[182:185], v[60:63]
	v_mfma_f32_16x16x32_bf16 v[56:59], v[152:155], v[182:185], v[56:59]
	v_mfma_f32_16x16x32_bf16 v[44:47], v[144:147], v[198:201], v[44:47]
	v_mfma_f32_16x16x32_bf16 v[40:43], v[152:155], v[198:201], v[40:43]
	v_mfma_f32_16x16x32_bf16 v[28:31], v[144:147], v[210:213], v[28:31]
	v_mfma_f32_16x16x32_bf16 v[24:27], v[152:155], v[210:213], v[24:27]
	v_mfma_f32_16x16x32_bf16 v[12:15], v[144:147], v[218:221], v[12:15]
	v_mfma_f32_16x16x32_bf16 v[8:11], v[152:155], v[218:221], v[8:11]
	v_mfma_f32_16x16x32_bf16 v[60:63], v[148:151], v[194:197], v[60:63]
	v_mfma_f32_16x16x32_bf16 v[56:59], v[162:165], v[194:197], v[56:59]
	v_mfma_f32_16x16x32_bf16 v[44:47], v[148:151], v[202:205], v[44:47]
	v_mfma_f32_16x16x32_bf16 v[40:43], v[162:165], v[202:205], v[40:43]
	v_mfma_f32_16x16x32_bf16 v[28:31], v[148:151], v[214:217], v[28:31]
	v_mfma_f32_16x16x32_bf16 v[24:27], v[162:165], v[214:217], v[24:27]
	v_mfma_f32_16x16x32_bf16 v[12:15], v[148:151], v[222:225], v[12:15]
	v_mfma_f32_16x16x32_bf16 v[8:11], v[162:165], v[222:225], v[8:11]
	s_setprio 0
	s_setprio 1
	v_mfma_f32_16x16x32_bf16 v[52:55], v[166:169], v[182:185], v[52:55]
	v_mfma_f32_16x16x32_bf16 v[48:51], v[174:177], v[182:185], v[48:51]
	v_mfma_f32_16x16x32_bf16 v[36:39], v[166:169], v[198:201], v[36:39]
	v_mfma_f32_16x16x32_bf16 v[32:35], v[174:177], v[198:201], v[32:35]
	v_mfma_f32_16x16x32_bf16 v[20:23], v[166:169], v[210:213], v[20:23]
	v_mfma_f32_16x16x32_bf16 v[16:19], v[174:177], v[210:213], v[16:19]
	v_mfma_f32_16x16x32_bf16 v[4:7], v[166:169], v[218:221], v[4:7]
	v_mfma_f32_16x16x32_bf16 v[0:3], v[174:177], v[218:221], v[0:3]
	v_mfma_f32_16x16x32_bf16 v[52:55], v[170:173], v[194:197], v[52:55]
	v_mfma_f32_16x16x32_bf16 v[48:51], v[178:181], v[194:197], v[48:51]
	v_mfma_f32_16x16x32_bf16 v[36:39], v[170:173], v[202:205], v[36:39]
	v_mfma_f32_16x16x32_bf16 v[32:35], v[178:181], v[202:205], v[32:35]
	v_mfma_f32_16x16x32_bf16 v[20:23], v[170:173], v[214:217], v[20:23]
	v_mfma_f32_16x16x32_bf16 v[16:19], v[178:181], v[214:217], v[16:19]
	v_mfma_f32_16x16x32_bf16 v[4:7], v[170:173], v[222:225], v[4:7]
	v_mfma_f32_16x16x32_bf16 v[0:3], v[178:181], v[222:225], v[0:3]
	s_setprio 0
	s_barrier
	s_add_i32 s41, 0, 0x18000
	s_add_i32 s42, 0, 0x1c000
	v_add_u32_e32 v162, s41, v159
	v_add_u32_e32 v178, s42, v159
	ds_read_b128 v[144:147], v162
	ds_read_b128 v[148:151], v162 offset:1024
	ds_read_b128 v[152:155], v162 offset:2048
	ds_read_b128 v[162:165], v162 offset:3072
	ds_read_b128 v[166:169], v178
	ds_read_b128 v[170:173], v178 offset:1024
	ds_read_b128 v[174:177], v178 offset:2048
	ds_read_b128 v[178:181], v178 offset:3072
	s_add_u32 s20, s20, 0x40000
	s_addc_u32 s21, s21, 0
	s_mov_b32 m0, s26
	v_lshl_add_u64 v[228:229], s[20:21], 0, v[128:129]
	ds_read_b128 v[182:185], v161 offset:32768
	ds_read_b128 v[194:197], v161 offset:33792
	ds_read_b128 v[198:201], v161 offset:34816
	ds_read_b128 v[202:205], v161 offset:35840
	ds_read_b128 v[210:213], v161 offset:36864
	ds_read_b128 v[214:217], v161 offset:37888
	ds_read_b128 v[218:221], v161 offset:38912
	ds_read_b128 v[222:225], v161 offset:39936
	global_load_lds_dwordx4 v[228:229], off
	v_lshl_add_u64 v[228:229], s[20:21], 0, v[132:133]
	s_mov_b32 m0, s27
	s_nop 0
	global_load_lds_dwordx4 v[228:229], off
	s_waitcnt vmcnt(8)
	s_waitcnt lgkmcnt(0)
	s_barrier
	s_setprio 1
	s_waitcnt lgkmcnt(0)
	v_mfma_f32_16x16x32_bf16 v[124:127], v[144:147], v[182:185], v[124:127]
	v_mfma_f32_16x16x32_bf16 v[120:123], v[152:155], v[182:185], v[120:123]
	v_mfma_f32_16x16x32_bf16 v[108:111], v[144:147], v[198:201], v[108:111]
	v_mfma_f32_16x16x32_bf16 v[104:107], v[152:155], v[198:201], v[104:107]
	v_mfma_f32_16x16x32_bf16 v[92:95], v[144:147], v[210:213], v[92:95]
	v_mfma_f32_16x16x32_bf16 v[88:91], v[152:155], v[210:213], v[88:91]
	v_mfma_f32_16x16x32_bf16 v[76:79], v[144:147], v[218:221], v[76:79]
	v_mfma_f32_16x16x32_bf16 v[72:75], v[152:155], v[218:221], v[72:75]
	v_mfma_f32_16x16x32_bf16 v[124:127], v[148:151], v[194:197], v[124:127]
	v_mfma_f32_16x16x32_bf16 v[120:123], v[162:165], v[194:197], v[120:123]
	v_mfma_f32_16x16x32_bf16 v[108:111], v[148:151], v[202:205], v[108:111]
	v_mfma_f32_16x16x32_bf16 v[104:107], v[162:165], v[202:205], v[104:107]
	v_mfma_f32_16x16x32_bf16 v[92:95], v[148:151], v[214:217], v[92:95]
	v_mfma_f32_16x16x32_bf16 v[88:91], v[162:165], v[214:217], v[88:91]
	v_mfma_f32_16x16x32_bf16 v[76:79], v[148:151], v[222:225], v[76:79]
	v_mfma_f32_16x16x32_bf16 v[72:75], v[162:165], v[222:225], v[72:75]
	s_setprio 0
	s_setprio 1
	v_mfma_f32_16x16x32_bf16 v[116:119], v[166:169], v[182:185], v[116:119]
	v_mfma_f32_16x16x32_bf16 v[112:115], v[174:177], v[182:185], v[112:115]
	v_mfma_f32_16x16x32_bf16 v[100:103], v[166:169], v[198:201], v[100:103]
	v_mfma_f32_16x16x32_bf16 v[96:99], v[174:177], v[198:201], v[96:99]
	v_mfma_f32_16x16x32_bf16 v[84:87], v[166:169], v[210:213], v[84:87]
	v_mfma_f32_16x16x32_bf16 v[80:83], v[174:177], v[210:213], v[80:83]
	v_mfma_f32_16x16x32_bf16 v[68:71], v[166:169], v[218:221], v[68:71]
	v_mfma_f32_16x16x32_bf16 v[64:67], v[174:177], v[218:221], v[64:67]
	v_mfma_f32_16x16x32_bf16 v[116:119], v[170:173], v[194:197], v[116:119]
	v_mfma_f32_16x16x32_bf16 v[112:115], v[178:181], v[194:197], v[112:115]
	v_mfma_f32_16x16x32_bf16 v[100:103], v[170:173], v[202:205], v[100:103]
	v_mfma_f32_16x16x32_bf16 v[96:99], v[178:181], v[202:205], v[96:99]
	v_mfma_f32_16x16x32_bf16 v[84:87], v[170:173], v[214:217], v[84:87]
	v_mfma_f32_16x16x32_bf16 v[80:83], v[178:181], v[214:217], v[80:83]
	v_mfma_f32_16x16x32_bf16 v[68:71], v[170:173], v[222:225], v[68:71]
	v_mfma_f32_16x16x32_bf16 v[64:67], v[178:181], v[222:225], v[64:67]
	s_setprio 0
	s_barrier
; #define PG8_STAGE(bufoff, gbase, voff) do { _Pragma("unroll") for (int _i = 0; _i < 2; ++_i) \
;         __builtin_amdgcn_global_load_lds((const unsigned*)((const char*)(gbase) + (voff)[_i]), (PG8_LAS unsigned*)(lds + (bufoff) + ldsw + _i * 8192), 16, 0, 0); } while (0)
; #define PG8_LDA(dst, b, h) do { _Pragma("unroll") for (int m = 0; m < 4; ++m) _Pragma("unroll") for (int k = 0; k < 2; ++k) dst[m][k] = *(const PG8_LAS bf16x8*)(lds + PG8_SA(b, h) + aoff + m * 2048 + k * 1024); } while (0)
; #define PG8_LDB(dst, b, h) do { _Pragma("unroll") for (int n = 0; n < 2; ++n) _Pragma("unroll") for (int k = 0; k < 2; ++k) dst[n][k] = *(const PG8_LAS bf16x8*)(lds + PG8_SB(b, h) + boff + n * 2048 + k * 1024); } while (0)
;     __device__ __forceinline__ void operator()(const f32x4 (&acc)[2][2][4][2], const Unit& u, int wr, int wc, int fr, int fq) const {
;         const int pn = u.pn; const int row0 = u.pm * BM + wr * 64 + fr;
;         if (pn < 8) {
;             const int X = 2 * (pn & 3) + (wc >> 1), dl = (wc & 1) * 32 + 8 * fq;
;             const float ksc = pn >= 4 ? 0.08838834764831845f : 1.f;
;             bf16_t* base = P + (size_t)(pn >> 2) * bstride + X * 128 + dl;
; #pragma unroll
;             for (int ai = 0; ai < 2; ++ai)
; #pragma unroll
;                 for (int m = 0; m < 4; ++m) { const int row = row0 + ai * HALF + m * 16;
;                     const int pidx = row < 16384 ? 16 + (row & 2047) : row < 16512 ? ((row - 16384) & 15) : row < 17536 ? 2064 + ((row - 16512) & 7) : 0;
;                     const f32x4* tp = (const f32x4*)(tab + ((size_t)pidx * 64 + dl) * 2);
;                     const f32x4 t0 = tp[0], t1 = tp[1], t2 = tp[2], t3 = tp[3];
; template <class Epi, class Sched, bool ALIGN_EPI = false, bool SP2 = false>
; __device__ __forceinline__ void gemm_phase(PG8_LAS unsigned char* lds, const Gemm g, const Sched& S, const Epi& E) {
;     ...
;             PG8_LDB(B0, 1, 0); PG8_LDB(B1, 1, 1); PG8_SCHED; PG8_LDA(At, 1, 0); PG8_STAGE(PG8_SA(0, 1), a2 + hstep, voffA);
;             PG8_WAIT_V(8); PG8_WAIT_L(0); PG8_BAR; PG8_MMA(0, 0, At, B0); PG8_MMA(0, 1, At, B1); PG8_BAR; PG8_SCHED;
;             PG8_LDA(At, 1, 1); PG8_STAGE(PG8_SB(1, 0), b3, voffB); PG8_STAGE(PG8_SB(1, 1), b3 + hstep, voffB); PG8_STAGE(PG8_SA(1, 0), a3, voffA);
;             PG8_WAIT_V(8); PG8_WAIT_L(0); PG8_BAR; PG8_MMA(1, 0, At, B0); PG8_MMA(1, 1, At, B1); PG8_BAR; PG8_SCHED;
	s_add_i32 s20, s41, s23
	v_lshl_add_u64 v[156:157], v[156:157], 0, s[46:47]
	s_mov_b32 m0, s20
	ds_read_b128 v[182:185], v161 offset:49152
	ds_read_b128 v[194:197], v161 offset:50176
	ds_read_b128 v[198:201], v161 offset:51200
	ds_read_b128 v[202:205], v161 offset:52224
	ds_read_b128 v[210:213], v161 offset:53248
	ds_read_b128 v[214:217], v161 offset:54272
	ds_read_b128 v[218:221], v161 offset:55296
	ds_read_b128 v[222:225], v161 offset:56320
	global_load_lds_dwordx4 v[156:157], off
	s_add_i32 m0, s20, 0x2000
	s_add_u32 s18, s18, 0x40080
	v_lshl_add_u64 v[156:157], v[186:187], 0, s[46:47]
	s_addc_u32 s19, s19, 0
	s_add_i32 s20, s42, s23
	global_load_lds_dwordx4 v[156:157], off
	v_lshl_add_u64 v[156:157], s[18:19], 0, v[130:131]
	s_mov_b32 m0, s20
	s_nop 0
	global_load_lds_dwordx4 v[156:157], off
	v_lshl_add_u64 v[156:157], s[18:19], 0, v[134:135]
	s_add_i32 m0, s20, 0x2000
	s_nop 0
	global_load_lds_dwordx4 v[156:157], off
	v_lshl_add_u64 v[156:157], v[190:191], 0, s[46:47]
	s_mov_b32 m0, s30
	s_nop 0
	global_load_lds_dwordx4 v[156:157], off
	v_lshl_add_u64 v[156:157], v[226:227], 0, s[46:47]
	s_mov_b32 m0, s31
	s_nop 0
	global_load_lds_dwordx4 v[156:157], off
	s_waitcnt vmcnt(8)
	s_waitcnt lgkmcnt(0)
	s_barrier
	s_setprio 1
	s_waitcnt lgkmcnt(0)
	v_mfma_f32_16x16x32_bf16 v[60:63], v[144:147], v[182:185], v[60:63]
	v_mfma_f32_16x16x32_bf16 v[56:59], v[152:155], v[182:185], v[56:59]
	v_mfma_f32_16x16x32_bf16 v[44:47], v[144:147], v[198:201], v[44:47]
	v_mfma_f32_16x16x32_bf16 v[40:43], v[152:155], v[198:201], v[40:43]
	v_mfma_f32_16x16x32_bf16 v[28:31], v[144:147], v[210:213], v[28:31]
	v_mfma_f32_16x16x32_bf16 v[24:27], v[152:155], v[210:213], v[24:27]
	v_mfma_f32_16x16x32_bf16 v[12:15], v[144:147], v[218:221], v[12:15]
	v_mfma_f32_16x16x32_bf16 v[8:11], v[152:155], v[218:221], v[8:11]
	v_mfma_f32_16x16x32_bf16 v[60:63], v[148:151], v[194:197], v[60:63]
	v_mfma_f32_16x16x32_bf16 v[56:59], v[162:165], v[194:197], v[56:59]
	v_mfma_f32_16x16x32_bf16 v[44:47], v[148:151], v[202:205], v[44:47]
	v_mfma_f32_16x16x32_bf16 v[40:43], v[162:165], v[202:205], v[40:43]
	v_mfma_f32_16x16x32_bf16 v[28:31], v[148:151], v[214:217], v[28:31]
	v_mfma_f32_16x16x32_bf16 v[24:27], v[162:165], v[214:217], v[24:27]
	v_mfma_f32_16x16x32_bf16 v[12:15], v[148:151], v[222:225], v[12:15]
	v_mfma_f32_16x16x32_bf16 v[8:11], v[162:165], v[222:225], v[8:11]
	s_setprio 0
	s_setprio 1
	v_mfma_f32_16x16x32_bf16 v[52:55], v[166:169], v[182:185], v[52:55]
	v_mfma_f32_16x16x32_bf16 v[48:51], v[174:177], v[182:185], v[48:51]
	v_mfma_f32_16x16x32_bf16 v[36:39], v[166:169], v[198:201], v[36:39]
	v_mfma_f32_16x16x32_bf16 v[32:35], v[174:177], v[198:201], v[32:35]
	v_mfma_f32_16x16x32_bf16 v[20:23], v[166:169], v[210:213], v[20:23]
	v_mfma_f32_16x16x32_bf16 v[16:19], v[174:177], v[210:213], v[16:19]
	v_mfma_f32_16x16x32_bf16 v[4:7], v[166:169], v[218:221], v[4:7]
	v_mfma_f32_16x16x32_bf16 v[0:3], v[174:177], v[218:221], v[0:3]
	v_mfma_f32_16x16x32_bf16 v[52:55], v[170:173], v[194:197], v[52:55]
	v_mfma_f32_16x16x32_bf16 v[48:51], v[178:181], v[194:197], v[48:51]
	v_mfma_f32_16x16x32_bf16 v[36:39], v[170:173], v[202:205], v[36:39]
	v_mfma_f32_16x16x32_bf16 v[32:35], v[178:181], v[202:205], v[32:35]
	v_mfma_f32_16x16x32_bf16 v[20:23], v[170:173], v[214:217], v[20:23]
	v_mfma_f32_16x16x32_bf16 v[16:19], v[178:181], v[214:217], v[16:19]
	v_mfma_f32_16x16x32_bf16 v[4:7], v[170:173], v[222:225], v[4:7]
	v_mfma_f32_16x16x32_bf16 v[0:3], v[178:181], v[222:225], v[0:3]
	s_setprio 0
	s_barrier
	s_add_i32 s40, s40, 2
	s_add_u32 s16, s16, 0x100
	s_addc_u32 s17, s17, 0
	s_add_u32 s38, s38, 0x100
	s_addc_u32 s39, s39, 0
	s_cmp_gt_u32 s40, 13
	s_cbranch_scc0 .LBB0_133
	s_cmp_gt_i32 s37, 7
	s_cbranch_scc1 .Lqk_nopre
	s_lshl_b32 s1, s0, 8
	s_add_i32 s1, s1, s28
	v_or_b32_e32 v144, s1, v158
	s_movk_i32 s96, 0x3fff
	s_movk_i32 s97, 0x4080
	s_movk_i32 s98, 0x4480
	v_mov_b32_e32 v155, 0
	v_mov_b32_e32 v156, v144
	v_and_b32_e32 v157, 0x7ff, v156
	v_cmp_gt_u32_e32 vcc, s98, v156
	v_add_u32_e32 v157, 16, v157
	s_nop 1
	v_cndmask_b32_e32 v222, 0, v160, vcc
	v_cmp_gt_u32_e32 vcc, s97, v156
	s_nop 1
	v_cndmask_b32_e32 v222, v222, v158, vcc
	v_cmp_lt_i32_e32 vcc, s96, v156
	s_nop 1
	v_cndmask_b32_e32 v157, v157, v222, vcc
	v_lshlrev_b32_e32 v154, 9, v157
	v_lshl_add_u64 v[150:151], v[138:139], 0, v[154:155]
	global_load_dwordx4 v[170:173], v[150:151], off offset:32
	global_load_dwordx4 v[174:177], v[150:151], off offset:48
	global_load_dwordx4 v[162:165], v[150:151], off
	global_load_dwordx4 v[166:169], v[150:151], off offset:16
	v_add_u32_e32 v156, 16, v144
	v_and_b32_e32 v157, 0x7ff, v156
	v_cmp_gt_u32_e32 vcc, s98, v156
	v_add_u32_e32 v157, 16, v157
	s_nop 1
	v_cndmask_b32_e32 v222, 0, v160, vcc
	v_cmp_gt_u32_e32 vcc, s97, v156
	s_nop 1
	v_cndmask_b32_e32 v222, v222, v158, vcc
	v_cmp_lt_i32_e32 vcc, s96, v156
	s_nop 1
	v_cndmask_b32_e32 v157, v157, v222, vcc
	v_lshlrev_b32_e32 v154, 9, v157
	v_lshl_add_u64 v[150:151], v[138:139], 0, v[154:155]
	global_load_dwordx4 v[194:197], v[150:151], off offset:32
	global_load_dwordx4 v[198:201], v[150:151], off offset:48
	global_load_dwordx4 v[178:181], v[150:151], off
	global_load_dwordx4 v[182:185], v[150:151], off offset:16
	v_add_u32_e32 v156, 32, v144
	v_and_b32_e32 v157, 0x7ff, v156
	v_cmp_gt_u32_e32 vcc, s98, v156
	v_add_u32_e32 v157, 16, v157
	s_nop 1
	v_cndmask_b32_e32 v222, 0, v160, vcc
	v_cmp_gt_u32_e32 vcc, s97, v156
	s_nop 1
	v_cndmask_b32_e32 v222, v222, v158, vcc
	v_cmp_lt_i32_e32 vcc, s96, v156
	s_nop 1
	v_cndmask_b32_e32 v157, v157, v222, vcc
	v_lshlrev_b32_e32 v154, 9, v157
	v_lshl_add_u64 v[150:151], v[138:139], 0, v[154:155]
	global_load_dwordx4 v[214:217], v[150:151], off offset:32
	global_load_dwordx4 v[218:221], v[150:151], off offset:48
	global_load_dwordx4 v[202:205], v[150:151], off
	global_load_dwordx4 v[210:213], v[150:151], off offset:16
.Lqk_nopre:
	s_and_b64 vcc, exec, s[6:7]
	s_cbranch_vccz .LBB0_136
	s_barrier

; __device__ __forceinline__ u32x4 pack8(const f32x4 a, const f32x4 b) { u32x4 w; w.x = cvt_pk_bf16(a[0], a[1]); w.y = cvt_pk_bf16(a[2], a[3]); w.z = cvt_pk_bf16(b[0], b[1]); w.w = cvt_pk_bf16(b[2], b[3]); return w; }
;     __device__ __forceinline__ void operator()(const f32x4 (&acc)[2][2][4][2], const Unit& u, int wr, int wc, int fr, int fq) const {
;         const int pn = u.pn; const int row0 = u.pm * BM + wr * 64 + fr;
;         if (pn < 8) {
;             const int X = 2 * (pn & 3) + (wc >> 1), dl = (wc & 1) * 32 + 8 * fq;
;             const float ksc = pn >= 4 ? 0.08838834764831845f : 1.f;
;             bf16_t* base = P + (size_t)(pn >> 2) * bstride + X * 128 + dl;
; #pragma unroll
;             for (int ai = 0; ai < 2; ++ai)
; #pragma unroll
;                 for (int m = 0; m < 4; ++m) { const int row = row0 + ai * HALF + m * 16;
;                     const int pidx = row < 16384 ? 16 + (row & 2047) : row < 16512 ? ((row - 16384) & 15) : row < 17536 ? 2064 + ((row - 16512) & 7) : 0;
;                     const f32x4* tp = (const f32x4*)(tab + ((size_t)pidx * 64 + dl) * 2);
;                     const f32x4 t0 = tp[0], t1 = tp[1], t2 = tp[2], t3 = tp[3];
;                     const f32x4 c0 = {t0.x, t0.z, t1.x, t1.z}, s0 = {t0.y, t0.w, t1.y, t1.w}, c1 = {t2.x, t2.z, t3.x, t3.z}, s1 = {t2.y, t2.w, t3.y, t3.w};
;                     const f32x4 a0 = acc[ai][0][m][0], a1 = acc[ai][0][m][1], b0 = acc[ai][1][m][0], b1 = acc[ai][1][m][1];
;                     const f32x4 o10 = (a0 * c0 - b0 * s0) * ksc, o11 = (a1 * c1 - b1 * s1) * ksc, o20 = (a0 * s0 + b0 * c0) * ksc, o21 = (a1 * s1 + b1 * c1) * ksc;
;                     bf16_t* rowp = base + (size_t)row * 1024;
;                     *(u32x4*)rowp = pack8(o10, o11); *(u32x4*)(rowp + 64) = pack8(o20, o21);
;                     if (m & 1) asm volatile("" ::: "memory"); }
.LBB0_141:
	s_lshl_b32 s0, s37, 1
	s_and_b32 s0, s0, 6
	s_or_b32 s0, s0, s34
	s_ashr_i32 s1, s37, 2
	s_mul_hi_i32 s11, s1, 0x2280000
	s_mul_i32 s1, s1, 0x2280000
	v_readlane_b32 s16, v254, 19
	s_add_u32 s1, s16, s1
	v_readlane_b32 s16, v254, 20
	s_addc_u32 s11, s16, s11
	s_lshl_b32 s0, s0, 8
	s_add_u32 s0, s1, s0
	s_addc_u32 s1, s11, 0
	s_cmp_gt_i32 s37, 3
	s_cselect_b32 s16, 0x3db504f3, 1.0
	v_lshl_add_u64 v[148:149], s[0:1], 0, v[188:189]
	v_mov_b32_e32 v146, s16
	s_waitcnt vmcnt(8)
	v_mul_f32_e32 v145, v116, v163
	v_mul_f32_e32 v147, v116, v162
	v_fma_f32 v145, v124, v162, -v145
	v_fmac_f32_e32 v147, v124, v163
	v_mul_f32_e32 v124, v146, v145
	v_mul_f32_e32 v116, v146, v147
	v_mul_f32_e32 v145, v117, v165
	v_mul_f32_e32 v147, v117, v164
	v_fma_f32 v145, v125, v164, -v145
	v_fmac_f32_e32 v147, v125, v165
	v_mul_f32_e32 v125, v146, v145
	v_mul_f32_e32 v117, v146, v147
	v_mul_f32_e32 v145, v118, v167
	v_mul_f32_e32 v147, v118, v166
	v_fma_f32 v145, v126, v166, -v145
	v_fmac_f32_e32 v147, v126, v167
	v_mul_f32_e32 v126, v146, v145
	v_mul_f32_e32 v118, v146, v147
	v_mul_f32_e32 v145, v119, v169
	v_mul_f32_e32 v147, v119, v168
	v_fma_f32 v145, v127, v168, -v145
	v_fmac_f32_e32 v147, v127, v169
	v_mul_f32_e32 v127, v146, v145
	v_mul_f32_e32 v119, v146, v147
	v_mul_f32_e32 v145, v112, v171
	v_mul_f32_e32 v147, v112, v170
	v_fma_f32 v145, v120, v170, -v145
	v_fmac_f32_e32 v147, v120, v171
	v_mul_f32_e32 v120, v146, v145
	v_mul_f32_e32 v112, v146, v147
	v_mul_f32_e32 v145, v113, v173
	v_mul_f32_e32 v147, v113, v172
	v_fma_f32 v145, v121, v172, -v145
	v_fmac_f32_e32 v147, v121, v173
	v_mul_f32_e32 v121, v146, v145
	v_mul_f32_e32 v113, v146, v147
	v_mul_f32_e32 v145, v114, v175
	v_mul_f32_e32 v147, v114, v174
	v_fma_f32 v145, v122, v174, -v145
	v_fmac_f32_e32 v147, v122, v175
	v_mul_f32_e32 v122, v146, v145
	v_mul_f32_e32 v114, v146, v147
	v_mul_f32_e32 v145, v115, v177
	v_mul_f32_e32 v147, v115, v176
	v_fma_f32 v145, v123, v176, -v145
	v_fmac_f32_e32 v147, v123, v177
	v_mul_f32_e32 v123, v146, v145
	v_mul_f32_e32 v115, v146, v147
	v_mov_b32_e32 v156, v144
	v_lshlrev_b32_e32 v154, 11, v156
	v_lshl_add_u64 v[152:153], v[148:149], 0, v[154:155]
	v_cvt_pk_bf16_f32 v162, v124, v125
	v_cvt_pk_bf16_f32 v163, v126, v127
	v_cvt_pk_bf16_f32 v164, v120, v121
	v_cvt_pk_bf16_f32 v165, v122, v123
	v_cvt_pk_bf16_f32 v166, v116, v117
	v_cvt_pk_bf16_f32 v167, v118, v119
	v_cvt_pk_bf16_f32 v168, v112, v113
	v_cvt_pk_bf16_f32 v169, v114, v115
	global_store_dwordx4 v[152:153], v[162:165], off
	global_store_dwordx4 v[152:153], v[166:169], off offset:128
	v_add_u32_e32 v156, 48, v144
	v_and_b32_e32 v157, 0x7ff, v156
	v_cmp_gt_u32_e32 vcc, s98, v156
	v_add_u32_e32 v157, 16, v157
	s_nop 1
	v_cndmask_b32_e32 v222, 0, v160, vcc
	v_cmp_gt_u32_e32 vcc, s97, v156
	s_nop 1
	v_cndmask_b32_e32 v222, v222, v158, vcc
	v_cmp_lt_i32_e32 vcc, s96, v156
	s_nop 1
	v_cndmask_b32_e32 v157, v157, v222, vcc
	v_lshlrev_b32_e32 v154, 9, v157
	v_lshl_add_u64 v[150:151], v[138:139], 0, v[154:155]
	global_load_dwordx4 v[170:173], v[150:151], off offset:32
	global_load_dwordx4 v[174:177], v[150:151], off offset:48
	global_load_dwordx4 v[162:165], v[150:151], off
	global_load_dwordx4 v[166:169], v[150:151], off offset:16
	s_waitcnt vmcnt(10)
	v_mul_f32_e32 v145, v100, v179
	v_mul_f32_e32 v147, v100, v178
	v_fma_f32 v145, v108, v178, -v145
	v_fmac_f32_e32 v147, v108, v179
	v_mul_f32_e32 v108, v146, v145
	v_mul_f32_e32 v100, v146, v147
	v_mul_f32_e32 v145, v101, v181
	v_mul_f32_e32 v147, v101, v180
	v_fma_f32 v145, v109, v180, -v145
	v_fmac_f32_e32 v147, v109, v181
	v_mul_f32_e32 v109, v146, v145
	v_mul_f32_e32 v101, v146, v147
	v_mul_f32_e32 v145, v102, v183
	v_mul_f32_e32 v147, v102, v182
	v_fma_f32 v145, v110, v182, -v145
	v_fmac_f32_e32 v147, v110, v183
	v_mul_f32_e32 v110, v146, v145
	v_mul_f32_e32 v102, v146, v147
	v_mul_f32_e32 v145, v103, v185
	v_mul_f32_e32 v147, v103, v184
	v_fma_f32 v145, v111, v184, -v145
	v_fmac_f32_e32 v147, v111, v185
	v_mul_f32_e32 v111, v146, v145
	v_mul_f32_e32 v103, v146, v147
	v_mul_f32_e32 v145, v96, v195
	v_mul_f32_e32 v147, v96, v194
	v_fma_f32 v145, v104, v194, -v145
	v_fmac_f32_e32 v147, v104, v195
	v_mul_f32_e32 v104, v146, v145
	v_mul_f32_e32 v96, v146, v147
	v_mul_f32_e32 v145, v97, v197
	v_mul_f32_e32 v147, v97, v196
	v_fma_f32 v145, v105, v196, -v145
	v_fmac_f32_e32 v147, v105, v197
	v_mul_f32_e32 v105, v146, v145
	v_mul_f32_e32 v97, v146, v147
	v_mul_f32_e32 v145, v98, v199
	v_mul_f32_e32 v147, v98, v198
	v_fma_f32 v145, v106, v198, -v145
	v_fmac_f32_e32 v147, v106, v199
	v_mul_f32_e32 v106, v146, v145
	v_mul_f32_e32 v98, v146, v147
	v_mul_f32_e32 v145, v99, v201
	v_mul_f32_e32 v147, v99, v200
	v_fma_f32 v145, v107, v200, -v145
	v_fmac_f32_e32 v147, v107, v201
	v_mul_f32_e32 v107, v146, v145
	v_mul_f32_e32 v99, v146, v147
	v_add_u32_e32 v156, 16, v144
	v_lshlrev_b32_e32 v154, 11, v156
	v_lshl_add_u64 v[152:153], v[148:149], 0, v[154:155]
	v_cvt_pk_bf16_f32 v178, v108, v109
	v_cvt_pk_bf16_f32 v179, v110, v111
	v_cvt_pk_bf16_f32 v180, v104, v105
	v_cvt_pk_bf16_f32 v181, v106, v107
	v_cvt_pk_bf16_f32 v182, v100, v101
	v_cvt_pk_bf16_f32 v183, v102, v103
	v_cvt_pk_bf16_f32 v184, v96, v97
	v_cvt_pk_bf16_f32 v185, v98, v99
	global_store_dwordx4 v[152:153], v[178:181], off
	global_store_dwordx4 v[152:153], v[182:185], off offset:128
	v_add_u32_e32 v156, 128, v144
	v_and_b32_e32 v157, 0x7ff, v156
	v_cmp_gt_u32_e32 vcc, s98, v156
	v_add_u32_e32 v157, 16, v157
	s_nop 1
	v_cndmask_b32_e32 v222, 0, v160, vcc
	v_cmp_gt_u32_e32 vcc, s97, v156
	s_nop 1
	v_cndmask_b32_e32 v222, v222, v158, vcc
	v_cmp_lt_i32_e32 vcc, s96, v156
	s_nop 1
	v_cndmask_b32_e32 v157, v157, v222, vcc
	v_lshlrev_b32_e32 v154, 9, v157
	v_lshl_add_u64 v[150:151], v[138:139], 0, v[154:155]
	global_load_dwordx4 v[194:197], v[150:151], off offset:32
	global_load_dwordx4 v[198:201], v[150:151], off offset:48
	global_load_dwordx4 v[178:181], v[150:151], off
	global_load_dwordx4 v[182:185], v[150:151], off offset:16
	s_waitcnt vmcnt(12)
; __device__ __forceinline__ u32x4 pack8(const f32x4 a, const f32x4 b) { u32x4 w; w.x = cvt_pk_bf16(a[0], a[1]); w.y = cvt_pk_bf16(a[2], a[3]); w.z = cvt_pk_bf16(b[0], b[1]); w.w = cvt_pk_bf16(b[2], b[3]); return w; }
;     __device__ __forceinline__ void operator()(const f32x4 (&acc)[2][2][4][2], const Unit& u, int wr, int wc, int fr, int fq) const {
;     ...
;                 for (int m = 0; m < 4; ++m) { const int row = row0 + ai * HALF + m * 16;
;                     const int pidx = row < 16384 ? 16 + (row & 2047) : row < 16512 ? ((row - 16384) & 15) : row < 17536 ? 2064 + ((row - 16512) & 7) : 0;
;                     const f32x4* tp = (const f32x4*)(tab + ((size_t)pidx * 64 + dl) * 2);
;                     const f32x4 t0 = tp[0], t1 = tp[1], t2 = tp[2], t3 = tp[3];
;                     const f32x4 c0 = {t0.x, t0.z, t1.x, t1.z}, s0 = {t0.y, t0.w, t1.y, t1.w}, c1 = {t2.x, t2.z, t3.x, t3.z}, s1 = {t2.y, t2.w, t3.y, t3.w};
;                     const f32x4 a0 = acc[ai][0][m][0], a1 = acc[ai][0][m][1], b0 = acc[ai][1][m][0], b1 = acc[ai][1][m][1];
;                     const f32x4 o10 = (a0 * c0 - b0 * s0) * ksc, o11 = (a1 * c1 - b1 * s1) * ksc, o20 = (a0 * s0 + b0 * c0) * ksc, o21 = (a1 * s1 + b1 * c1) * ksc;
;                     bf16_t* rowp = base + (size_t)row * 1024;
;                     *(u32x4*)rowp = pack8(o10, o11); *(u32x4*)(rowp + 64) = pack8(o20, o21);
;                     if (m & 1) asm volatile("" ::: "memory"); }
	v_mul_f32_e32 v145, v84, v203
	v_mul_f32_e32 v147, v84, v202
	v_fma_f32 v145, v92, v202, -v145
	v_fmac_f32_e32 v147, v92, v203
	v_mul_f32_e32 v92, v146, v145
	v_mul_f32_e32 v84, v146, v147
	v_mul_f32_e32 v145, v85, v205
	v_mul_f32_e32 v147, v85, v204
	v_fma_f32 v145, v93, v204, -v145
	v_fmac_f32_e32 v147, v93, v205
	v_mul_f32_e32 v93, v146, v145
	v_mul_f32_e32 v85, v146, v147
	v_mul_f32_e32 v145, v86, v211
	v_mul_f32_e32 v147, v86, v210
	v_fma_f32 v145, v94, v210, -v145
	v_fmac_f32_e32 v147, v94, v211
	v_mul_f32_e32 v94, v146, v145
	v_mul_f32_e32 v86, v146, v147
	v_mul_f32_e32 v145, v87, v213
	v_mul_f32_e32 v147, v87, v212
	v_fma_f32 v145, v95, v212, -v145
	v_fmac_f32_e32 v147, v95, v213
	v_mul_f32_e32 v95, v146, v145
	v_mul_f32_e32 v87, v146, v147
	v_mul_f32_e32 v145, v80, v215
	v_mul_f32_e32 v147, v80, v214
	v_fma_f32 v145, v88, v214, -v145
	v_fmac_f32_e32 v147, v88, v215
	v_mul_f32_e32 v88, v146, v145
	v_mul_f32_e32 v80, v146, v147
	v_mul_f32_e32 v145, v81, v217
	v_mul_f32_e32 v147, v81, v216
	v_fma_f32 v145, v89, v216, -v145
	v_fmac_f32_e32 v147, v89, v217
	v_mul_f32_e32 v89, v146, v145
	v_mul_f32_e32 v81, v146, v147
	v_mul_f32_e32 v145, v82, v219
	v_mul_f32_e32 v147, v82, v218
	v_fma_f32 v145, v90, v218, -v145
	v_fmac_f32_e32 v147, v90, v219
	v_mul_f32_e32 v90, v146, v145
	v_mul_f32_e32 v82, v146, v147
	v_mul_f32_e32 v145, v83, v221
	v_mul_f32_e32 v147, v83, v220
	v_fma_f32 v145, v91, v220, -v145
	v_fmac_f32_e32 v147, v91, v221
	v_mul_f32_e32 v91, v146, v145
	v_mul_f32_e32 v83, v146, v147
	v_add_u32_e32 v156, 32, v144
	v_lshlrev_b32_e32 v154, 11, v156
	v_lshl_add_u64 v[152:153], v[148:149], 0, v[154:155]
	v_cvt_pk_bf16_f32 v202, v92, v93
	v_cvt_pk_bf16_f32 v203, v94, v95
	v_cvt_pk_bf16_f32 v204, v88, v89
	v_cvt_pk_bf16_f32 v205, v90, v91
	v_cvt_pk_bf16_f32 v210, v84, v85
	v_cvt_pk_bf16_f32 v211, v86, v87
	v_cvt_pk_bf16_f32 v212, v80, v81
	v_cvt_pk_bf16_f32 v213, v82, v83
	global_store_dwordx4 v[152:153], v[202:205], off
	global_store_dwordx4 v[152:153], v[210:213], off offset:128
	v_add_u32_e32 v156, 144, v144
	v_and_b32_e32 v157, 0x7ff, v156
	v_cmp_gt_u32_e32 vcc, s98, v156
	v_add_u32_e32 v157, 16, v157
	s_nop 1
	v_cndmask_b32_e32 v222, 0, v160, vcc
	v_cmp_gt_u32_e32 vcc, s97, v156
	s_nop 1
	v_cndmask_b32_e32 v222, v222, v158, vcc
	v_cmp_lt_i32_e32 vcc, s96, v156
	s_nop 1
	v_cndmask_b32_e32 v157, v157, v222, vcc
	v_lshlrev_b32_e32 v154, 9, v157
	v_lshl_add_u64 v[150:151], v[138:139], 0, v[154:155]
	global_load_dwordx4 v[214:217], v[150:151], off offset:32
	global_load_dwordx4 v[218:221], v[150:151], off offset:48
	global_load_dwordx4 v[202:205], v[150:151], off
	global_load_dwordx4 v[210:213], v[150:151], off offset:16
	s_waitcnt vmcnt(12)
	v_mul_f32_e32 v145, v68, v163
	v_mul_f32_e32 v147, v68, v162
	v_fma_f32 v145, v76, v162, -v145
	v_fmac_f32_e32 v147, v76, v163
	v_mul_f32_e32 v76, v146, v145
	v_mul_f32_e32 v68, v146, v147
	v_mul_f32_e32 v145, v69, v165
	v_mul_f32_e32 v147, v69, v164
	v_fma_f32 v145, v77, v164, -v145
	v_fmac_f32_e32 v147, v77, v165
	v_mul_f32_e32 v77, v146, v145
	v_mul_f32_e32 v69, v146, v147
	v_mul_f32_e32 v145, v70, v167
	v_mul_f32_e32 v147, v70, v166
	v_fma_f32 v145, v78, v166, -v145
	v_fmac_f32_e32 v147, v78, v167
	v_mul_f32_e32 v78, v146, v145
	v_mul_f32_e32 v70, v146, v147
	v_mul_f32_e32 v145, v71, v169
	v_mul_f32_e32 v147, v71, v168
	v_fma_f32 v145, v79, v168, -v145
	v_fmac_f32_e32 v147, v79, v169
	v_mul_f32_e32 v79, v146, v145
	v_mul_f32_e32 v71, v146, v147
	v_mul_f32_e32 v145, v64, v171
	v_mul_f32_e32 v147, v64, v170
	v_fma_f32 v145, v72, v170, -v145
	v_fmac_f32_e32 v147, v72, v171
	v_mul_f32_e32 v72, v146, v145
	v_mul_f32_e32 v64, v146, v147
	v_mul_f32_e32 v145, v65, v173
	v_mul_f32_e32 v147, v65, v172
	v_fma_f32 v145, v73, v172, -v145
	v_fmac_f32_e32 v147, v73, v173
	v_mul_f32_e32 v73, v146, v145
	v_mul_f32_e32 v65, v146, v147
	v_mul_f32_e32 v145, v66, v175
	v_mul_f32_e32 v147, v66, v174
	v_fma_f32 v145, v74, v174, -v145
	v_fmac_f32_e32 v147, v74, v175
	v_mul_f32_e32 v74, v146, v145
	v_mul_f32_e32 v66, v146, v147
	v_mul_f32_e32 v145, v67, v177
	v_mul_f32_e32 v147, v67, v176
	v_fma_f32 v145, v75, v176, -v145
	v_fmac_f32_e32 v147, v75, v177
	v_mul_f32_e32 v75, v146, v145
	v_mul_f32_e32 v67, v146, v147
	v_add_u32_e32 v156, 48, v144
	v_lshlrev_b32_e32 v154, 11, v156
	v_lshl_add_u64 v[152:153], v[148:149], 0, v[154:155]
	v_cvt_pk_bf16_f32 v162, v76, v77
	v_cvt_pk_bf16_f32 v163, v78, v79
	v_cvt_pk_bf16_f32 v164, v72, v73
	v_cvt_pk_bf16_f32 v165, v74, v75
	v_cvt_pk_bf16_f32 v166, v68, v69
	v_cvt_pk_bf16_f32 v167, v70, v71
	v_cvt_pk_bf16_f32 v168, v64, v65
	v_cvt_pk_bf16_f32 v169, v66, v67
	global_store_dwordx4 v[152:153], v[162:165], off
	global_store_dwordx4 v[152:153], v[166:169], off offset:128
	v_add_u32_e32 v156, 160, v144
	v_and_b32_e32 v157, 0x7ff, v156
	v_cmp_gt_u32_e32 vcc, s98, v156
	v_add_u32_e32 v157, 16, v157
	s_nop 1
	v_cndmask_b32_e32 v222, 0, v160, vcc
	v_cmp_gt_u32_e32 vcc, s97, v156
	s_nop 1
	v_cndmask_b32_e32 v222, v222, v158, vcc
	v_cmp_lt_i32_e32 vcc, s96, v156
	s_nop 1
	v_cndmask_b32_e32 v157, v157, v222, vcc
	v_lshlrev_b32_e32 v154, 9, v157
	v_lshl_add_u64 v[150:151], v[138:139], 0, v[154:155]
	global_load_dwordx4 v[170:173], v[150:151], off offset:32
	global_load_dwordx4 v[174:177], v[150:151], off offset:48
	global_load_dwordx4 v[162:165], v[150:151], off
	global_load_dwordx4 v[166:169], v[150:151], off offset:16
	s_waitcnt vmcnt(12)
; __device__ __forceinline__ u32x4 pack8(const f32x4 a, const f32x4 b) { u32x4 w; w.x = cvt_pk_bf16(a[0], a[1]); w.y = cvt_pk_bf16(a[2], a[3]); w.z = cvt_pk_bf16(b[0], b[1]); w.w = cvt_pk_bf16(b[2], b[3]); return w; }
;     __device__ __forceinline__ void operator()(const f32x4 (&acc)[2][2][4][2], const Unit& u, int wr, int wc, int fr, int fq) const {
;     ...
;                 for (int m = 0; m < 4; ++m) { const int row = row0 + ai * HALF + m * 16;
;                     const int pidx = row < 16384 ? 16 + (row & 2047) : row < 16512 ? ((row - 16384) & 15) : row < 17536 ? 2064 + ((row - 16512) & 7) : 0;
;                     const f32x4* tp = (const f32x4*)(tab + ((size_t)pidx * 64 + dl) * 2);
;                     const f32x4 t0 = tp[0], t1 = tp[1], t2 = tp[2], t3 = tp[3];
;                     const f32x4 c0 = {t0.x, t0.z, t1.x, t1.z}, s0 = {t0.y, t0.w, t1.y, t1.w}, c1 = {t2.x, t2.z, t3.x, t3.z}, s1 = {t2.y, t2.w, t3.y, t3.w};
;                     const f32x4 a0 = acc[ai][0][m][0], a1 = acc[ai][0][m][1], b0 = acc[ai][1][m][0], b1 = acc[ai][1][m][1];
;                     const f32x4 o10 = (a0 * c0 - b0 * s0) * ksc, o11 = (a1 * c1 - b1 * s1) * ksc, o20 = (a0 * s0 + b0 * c0) * ksc, o21 = (a1 * s1 + b1 * c1) * ksc;
;                     bf16_t* rowp = base + (size_t)row * 1024;
;                     *(u32x4*)rowp = pack8(o10, o11); *(u32x4*)(rowp + 64) = pack8(o20, o21);
;                     if (m & 1) asm volatile("" ::: "memory"); }
	v_mul_f32_e32 v145, v52, v179
	v_mul_f32_e32 v147, v52, v178
	v_fma_f32 v145, v60, v178, -v145
	v_fmac_f32_e32 v147, v60, v179
	v_mul_f32_e32 v60, v146, v145
	v_mul_f32_e32 v52, v146, v147
	v_mul_f32_e32 v145, v53, v181
	v_mul_f32_e32 v147, v53, v180
	v_fma_f32 v145, v61, v180, -v145
	v_fmac_f32_e32 v147, v61, v181
	v_mul_f32_e32 v61, v146, v145
	v_mul_f32_e32 v53, v146, v147
	v_mul_f32_e32 v145, v54, v183
	v_mul_f32_e32 v147, v54, v182
	v_fma_f32 v145, v62, v182, -v145
	v_fmac_f32_e32 v147, v62, v183
	v_mul_f32_e32 v62, v146, v145
	v_mul_f32_e32 v54, v146, v147
	v_mul_f32_e32 v145, v55, v185
	v_mul_f32_e32 v147, v55, v184
	v_fma_f32 v145, v63, v184, -v145
	v_fmac_f32_e32 v147, v63, v185
	v_mul_f32_e32 v63, v146, v145
	v_mul_f32_e32 v55, v146, v147
	v_mul_f32_e32 v145, v48, v195
	v_mul_f32_e32 v147, v48, v194
	v_fma_f32 v145, v56, v194, -v145
	v_fmac_f32_e32 v147, v56, v195
	v_mul_f32_e32 v56, v146, v145
	v_mul_f32_e32 v48, v146, v147
	v_mul_f32_e32 v145, v49, v197
	v_mul_f32_e32 v147, v49, v196
	v_fma_f32 v145, v57, v196, -v145
	v_fmac_f32_e32 v147, v57, v197
	v_mul_f32_e32 v57, v146, v145
	v_mul_f32_e32 v49, v146, v147
	v_mul_f32_e32 v145, v50, v199
	v_mul_f32_e32 v147, v50, v198
	v_fma_f32 v145, v58, v198, -v145
	v_fmac_f32_e32 v147, v58, v199
	v_mul_f32_e32 v58, v146, v145
	v_mul_f32_e32 v50, v146, v147
	v_mul_f32_e32 v145, v51, v201
	v_mul_f32_e32 v147, v51, v200
	v_fma_f32 v145, v59, v200, -v145
	v_fmac_f32_e32 v147, v59, v201
	v_mul_f32_e32 v59, v146, v145
	v_mul_f32_e32 v51, v146, v147
	v_add_u32_e32 v156, 128, v144
	v_lshlrev_b32_e32 v154, 11, v156
	v_lshl_add_u64 v[152:153], v[148:149], 0, v[154:155]
	v_cvt_pk_bf16_f32 v178, v60, v61
	v_cvt_pk_bf16_f32 v179, v62, v63
	v_cvt_pk_bf16_f32 v180, v56, v57
	v_cvt_pk_bf16_f32 v181, v58, v59
	v_cvt_pk_bf16_f32 v182, v52, v53
	v_cvt_pk_bf16_f32 v183, v54, v55
	v_cvt_pk_bf16_f32 v184, v48, v49
	v_cvt_pk_bf16_f32 v185, v50, v51
	global_store_dwordx4 v[152:153], v[178:181], off
	global_store_dwordx4 v[152:153], v[182:185], off offset:128
	v_add_u32_e32 v156, 176, v144
	v_and_b32_e32 v157, 0x7ff, v156
	v_cmp_gt_u32_e32 vcc, s98, v156
	v_add_u32_e32 v157, 16, v157
	s_nop 1
	v_cndmask_b32_e32 v222, 0, v160, vcc
	v_cmp_gt_u32_e32 vcc, s97, v156
	s_nop 1
	v_cndmask_b32_e32 v222, v222, v158, vcc
	v_cmp_lt_i32_e32 vcc, s96, v156
	s_nop 1
	v_cndmask_b32_e32 v157, v157, v222, vcc
	v_lshlrev_b32_e32 v154, 9, v157
	v_lshl_add_u64 v[150:151], v[138:139], 0, v[154:155]
	global_load_dwordx4 v[194:197], v[150:151], off offset:32
	global_load_dwordx4 v[198:201], v[150:151], off offset:48
	global_load_dwordx4 v[178:181], v[150:151], off
	global_load_dwordx4 v[182:185], v[150:151], off offset:16
	s_waitcnt vmcnt(12)
	v_mul_f32_e32 v145, v36, v203
	v_mul_f32_e32 v147, v36, v202
	v_fma_f32 v145, v44, v202, -v145
	v_fmac_f32_e32 v147, v44, v203
	v_mul_f32_e32 v44, v146, v145
	v_mul_f32_e32 v36, v146, v147
	v_mul_f32_e32 v145, v37, v205
	v_mul_f32_e32 v147, v37, v204
	v_fma_f32 v145, v45, v204, -v145
	v_fmac_f32_e32 v147, v45, v205
	v_mul_f32_e32 v45, v146, v145
	v_mul_f32_e32 v37, v146, v147
	v_mul_f32_e32 v145, v38, v211
	v_mul_f32_e32 v147, v38, v210
	v_fma_f32 v145, v46, v210, -v145
	v_fmac_f32_e32 v147, v46, v211
	v_mul_f32_e32 v46, v146, v145
	v_mul_f32_e32 v38, v146, v147
	v_mul_f32_e32 v145, v39, v213
	v_mul_f32_e32 v147, v39, v212
	v_fma_f32 v145, v47, v212, -v145
	v_fmac_f32_e32 v147, v47, v213
	v_mul_f32_e32 v47, v146, v145
	v_mul_f32_e32 v39, v146, v147
	v_mul_f32_e32 v145, v32, v215
	v_mul_f32_e32 v147, v32, v214
	v_fma_f32 v145, v40, v214, -v145
	v_fmac_f32_e32 v147, v40, v215
	v_mul_f32_e32 v40, v146, v145
	v_mul_f32_e32 v32, v146, v147
	v_mul_f32_e32 v145, v33, v217
	v_mul_f32_e32 v147, v33, v216
	v_fma_f32 v145, v41, v216, -v145
	v_fmac_f32_e32 v147, v41, v217
	v_mul_f32_e32 v41, v146, v145
	v_mul_f32_e32 v33, v146, v147
	v_mul_f32_e32 v145, v34, v219
	v_mul_f32_e32 v147, v34, v218
	v_fma_f32 v145, v42, v218, -v145
	v_fmac_f32_e32 v147, v42, v219
	v_mul_f32_e32 v42, v146, v145
	v_mul_f32_e32 v34, v146, v147
	v_mul_f32_e32 v145, v35, v221
	v_mul_f32_e32 v147, v35, v220
	v_fma_f32 v145, v43, v220, -v145
	v_fmac_f32_e32 v147, v43, v221
	v_mul_f32_e32 v43, v146, v145
	v_mul_f32_e32 v35, v146, v147
	v_add_u32_e32 v156, 144, v144
	v_lshlrev_b32_e32 v154, 11, v156
	v_lshl_add_u64 v[152:153], v[148:149], 0, v[154:155]
	v_cvt_pk_bf16_f32 v202, v44, v45
	v_cvt_pk_bf16_f32 v203, v46, v47
	v_cvt_pk_bf16_f32 v204, v40, v41
	v_cvt_pk_bf16_f32 v205, v42, v43
	v_cvt_pk_bf16_f32 v210, v36, v37
	v_cvt_pk_bf16_f32 v211, v38, v39
	v_cvt_pk_bf16_f32 v212, v32, v33
	v_cvt_pk_bf16_f32 v213, v34, v35
	global_store_dwordx4 v[152:153], v[202:205], off
	global_store_dwordx4 v[152:153], v[210:213], off offset:128
	s_waitcnt vmcnt(8)
; __device__ __forceinline__ u32x4 pack8(const f32x4 a, const f32x4 b) { u32x4 w; w.x = cvt_pk_bf16(a[0], a[1]); w.y = cvt_pk_bf16(a[2], a[3]); w.z = cvt_pk_bf16(b[0], b[1]); w.w = cvt_pk_bf16(b[2], b[3]); return w; }
;     __device__ __forceinline__ void operator()(const f32x4 (&acc)[2][2][4][2], const Unit& u, int wr, int wc, int fr, int fq) const {
;     ...
;                 for (int m = 0; m < 4; ++m) { const int row = row0 + ai * HALF + m * 16;
;                     const int pidx = row < 16384 ? 16 + (row & 2047) : row < 16512 ? ((row - 16384) & 15) : row < 17536 ? 2064 + ((row - 16512) & 7) : 0;
;                     const f32x4* tp = (const f32x4*)(tab + ((size_t)pidx * 64 + dl) * 2);
;                     const f32x4 t0 = tp[0], t1 = tp[1], t2 = tp[2], t3 = tp[3];
;                     const f32x4 c0 = {t0.x, t0.z, t1.x, t1.z}, s0 = {t0.y, t0.w, t1.y, t1.w}, c1 = {t2.x, t2.z, t3.x, t3.z}, s1 = {t2.y, t2.w, t3.y, t3.w};
;                     const f32x4 a0 = acc[ai][0][m][0], a1 = acc[ai][0][m][1], b0 = acc[ai][1][m][0], b1 = acc[ai][1][m][1];
;                     const f32x4 o10 = (a0 * c0 - b0 * s0) * ksc, o11 = (a1 * c1 - b1 * s1) * ksc, o20 = (a0 * s0 + b0 * c0) * ksc, o21 = (a1 * s1 + b1 * c1) * ksc;
;                     bf16_t* rowp = base + (size_t)row * 1024;
;                     *(u32x4*)rowp = pack8(o10, o11); *(u32x4*)(rowp + 64) = pack8(o20, o21);
;                     if (m & 1) asm volatile("" ::: "memory"); }
	v_mul_f32_e32 v145, v20, v163
	v_mul_f32_e32 v147, v20, v162
	v_fma_f32 v145, v28, v162, -v145
	v_fmac_f32_e32 v147, v28, v163
	v_mul_f32_e32 v28, v146, v145
	v_mul_f32_e32 v20, v146, v147
	v_mul_f32_e32 v145, v21, v165
	v_mul_f32_e32 v147, v21, v164
	v_fma_f32 v145, v29, v164, -v145
	v_fmac_f32_e32 v147, v29, v165
	v_mul_f32_e32 v29, v146, v145
	v_mul_f32_e32 v21, v146, v147
	v_mul_f32_e32 v145, v22, v167
	v_mul_f32_e32 v147, v22, v166
	v_fma_f32 v145, v30, v166, -v145
	v_fmac_f32_e32 v147, v30, v167
	v_mul_f32_e32 v30, v146, v145
	v_mul_f32_e32 v22, v146, v147
	v_mul_f32_e32 v145, v23, v169
	v_mul_f32_e32 v147, v23, v168
	v_fma_f32 v145, v31, v168, -v145
	v_fmac_f32_e32 v147, v31, v169
	v_mul_f32_e32 v31, v146, v145
	v_mul_f32_e32 v23, v146, v147
	v_mul_f32_e32 v145, v16, v171
	v_mul_f32_e32 v147, v16, v170
	v_fma_f32 v145, v24, v170, -v145
	v_fmac_f32_e32 v147, v24, v171
	v_mul_f32_e32 v24, v146, v145
	v_mul_f32_e32 v16, v146, v147
	v_mul_f32_e32 v145, v17, v173
	v_mul_f32_e32 v147, v17, v172
	v_fma_f32 v145, v25, v172, -v145
	v_fmac_f32_e32 v147, v25, v173
	v_mul_f32_e32 v25, v146, v145
	v_mul_f32_e32 v17, v146, v147
	v_mul_f32_e32 v145, v18, v175
	v_mul_f32_e32 v147, v18, v174
	v_fma_f32 v145, v26, v174, -v145
	v_fmac_f32_e32 v147, v26, v175
	v_mul_f32_e32 v26, v146, v145
	v_mul_f32_e32 v18, v146, v147
	v_mul_f32_e32 v145, v19, v177
	v_mul_f32_e32 v147, v19, v176
	v_fma_f32 v145, v27, v176, -v145
	v_fmac_f32_e32 v147, v27, v177
	v_mul_f32_e32 v27, v146, v145
	v_mul_f32_e32 v19, v146, v147
	v_add_u32_e32 v156, 160, v144
	v_lshlrev_b32_e32 v154, 11, v156
	v_lshl_add_u64 v[152:153], v[148:149], 0, v[154:155]
	v_cvt_pk_bf16_f32 v162, v28, v29
	v_cvt_pk_bf16_f32 v163, v30, v31
	v_cvt_pk_bf16_f32 v164, v24, v25
	v_cvt_pk_bf16_f32 v165, v26, v27
	v_cvt_pk_bf16_f32 v166, v20, v21
	v_cvt_pk_bf16_f32 v167, v22, v23
	v_cvt_pk_bf16_f32 v168, v16, v17
	v_cvt_pk_bf16_f32 v169, v18, v19
	global_store_dwordx4 v[152:153], v[162:165], off
	global_store_dwordx4 v[152:153], v[166:169], off offset:128
	s_waitcnt vmcnt(4)
	v_mul_f32_e32 v145, v4, v179
	v_mul_f32_e32 v147, v4, v178
	v_fma_f32 v145, v12, v178, -v145
	v_fmac_f32_e32 v147, v12, v179
	v_mul_f32_e32 v12, v146, v145
	v_mul_f32_e32 v4, v146, v147
	v_mul_f32_e32 v145, v5, v181
	v_mul_f32_e32 v147, v5, v180
	v_fma_f32 v145, v13, v180, -v145
	v_fmac_f32_e32 v147, v13, v181
	v_mul_f32_e32 v13, v146, v145
	v_mul_f32_e32 v5, v146, v147
	v_mul_f32_e32 v145, v6, v183
	v_mul_f32_e32 v147, v6, v182
	v_fma_f32 v145, v14, v182, -v145
	v_fmac_f32_e32 v147, v14, v183
	v_mul_f32_e32 v14, v146, v145
	v_mul_f32_e32 v6, v146, v147
	v_mul_f32_e32 v145, v7, v185
	v_mul_f32_e32 v147, v7, v184
	v_fma_f32 v145, v15, v184, -v145
	v_fmac_f32_e32 v147, v15, v185
	v_mul_f32_e32 v15, v146, v145
	v_mul_f32_e32 v7, v146, v147
	v_mul_f32_e32 v145, v0, v195
	v_mul_f32_e32 v147, v0, v194
	v_fma_f32 v145, v8, v194, -v145
	v_fmac_f32_e32 v147, v8, v195
	v_mul_f32_e32 v8, v146, v145
	v_mul_f32_e32 v0, v146, v147
	v_mul_f32_e32 v145, v1, v197
	v_mul_f32_e32 v147, v1, v196
	v_fma_f32 v145, v9, v196, -v145
	v_fmac_f32_e32 v147, v9, v197
	v_mul_f32_e32 v9, v146, v145
	v_mul_f32_e32 v1, v146, v147
	v_mul_f32_e32 v145, v2, v199
	v_mul_f32_e32 v147, v2, v198
	v_fma_f32 v145, v10, v198, -v145
	v_fmac_f32_e32 v147, v10, v199
	v_mul_f32_e32 v10, v146, v145
	v_mul_f32_e32 v2, v146, v147
	v_mul_f32_e32 v145, v3, v201
	v_mul_f32_e32 v147, v3, v200
	v_fma_f32 v145, v11, v200, -v145
	v_fmac_f32_e32 v147, v11, v201
	v_mul_f32_e32 v11, v146, v145
	v_mul_f32_e32 v3, v146, v147
	v_add_u32_e32 v156, 176, v144
	v_lshlrev_b32_e32 v154, 11, v156
	v_lshl_add_u64 v[152:153], v[148:149], 0, v[154:155]
	v_cvt_pk_bf16_f32 v178, v12, v13
	v_cvt_pk_bf16_f32 v179, v14, v15
	v_cvt_pk_bf16_f32 v180, v8, v9
	v_cvt_pk_bf16_f32 v181, v10, v11
	v_cvt_pk_bf16_f32 v182, v4, v5
	v_cvt_pk_bf16_f32 v183, v6, v7
	v_cvt_pk_bf16_f32 v184, v0, v1
	v_cvt_pk_bf16_f32 v185, v2, v3
	global_store_dwordx4 v[152:153], v[178:181], off
	global_store_dwordx4 v[152:153], v[182:185], off offset:128
	s_andn2_b64 vcc, exec, s[4:5]
	s_mov_b64 s[0:1], -1
	s_cbranch_vccnz .LBB0_127
	s_branch .LBB0_261
